# static priority raise (asm guide 7.4): s_setprio 1 for waves 4-7 for the whole attention phase, reset at its end; on top of v34
# speedup vs baseline: 1.0042x; 1.0042x over previous
; #define LAS __attribute__((address_space(3)))
; __device__ __forceinline__ void attn_phase(LAS unsigned char* lds, const bf16_t* Q, const bf16_t* Kb, const bf16_t* VT, const bf16_t* Zs, bf16_t* OZ, int vcu, int G) {
;     const int tid = threadIdx.x, lane = tid & 63, w = __builtin_amdgcn_readfirstlane(tid >> 6), ql = lane & 31, hi = lane >> 5;
;     constexpr float STOP = 5.421010862427522e-20f;
;     LAS unsigned char* KL = lds;
;     LAS unsigned char* VL = lds + 49152;
;     constexpr int NU = BATCH * 16 * (SEQ / 256);
;     u32x4 sk[6], sv[6];
;     ...
;     if (vcu < NU) ATT_LOAD_STAGE(vcu);
.LBB0_536:
	s_cmp_lt_i32 s54, 8
	s_cselect_b64 s[4:5], -1, 0
	s_and_b64 s[70:71], s[4:5], s[0:1]
	s_andn2_b64 vcc, exec, s[70:71]
	s_cbranch_vccnz .LBB0_557
	s_cmpk_gt_i32 s84, 0x3ff
	v_readfirstlane_b32 s0, v0
	s_cbranch_scc1 .LBB0_557
	s_mov_b32 s98, 0x42fc0000
	s_lshr_b32 s85, s0, 6
	s_cmp_ge_u32 s85, 4
	s_cbranch_scc0 .Lp7_prio_done
	s_setprio 1
.Lp7_prio_done:
	s_and_b32 s100, s84, 7
	s_bfe_u32 s99, s84, 0x20005
	s_lshl_b32 s99, s99, 3
	s_or_b32 s100, s100, s99
	s_bfe_u32 s99, s84, 0x20003
	s_lshl_b32 s99, s99, 5
	s_or_b32 s100, s100, s99
	s_bfe_u32 s99, s84, 0x20008
	s_lshl_b32 s99, s99, 7
	s_or_b32 s100, s100, s99
	s_bfe_u32 s99, s84, 0x10007
	s_lshl_b32 s99, s99, 9
	s_or_b32 s100, s100, s99
	s_ashr_i32 s0, s100, 9
	s_lshl_b32 s8, s100, 8
	s_ashr_i32 s1, s0, 31
	s_and_b32 s8, s8, 0x1f00
	s_bfe_u32 s14, s100, 0x40005
	s_lshl_b64 s[4:5], s[0:1], 13
	s_add_i32 s9, s8, 0xffffff80
	s_cmp_lg_u32 s8, 0
	s_cselect_b32 s8, s9, 0
	s_ashr_i32 s9, s8, 31
	s_add_u32 s10, s4, s8
	s_addc_u32 s11, s5, s9
	s_lshl_b32 s4, s14, 7
	v_lshrrev_b32_e32 v146, 3, v0
	s_waitcnt vmcnt(0)
	v_or_b32_e32 v9, 0x200, v0
	s_add_u32 s12, s6, s4
	v_lshlrev_b32_e32 v8, 4, v0
	v_or_b32_e32 v4, s10, v146
	v_mov_b32_e32 v5, s11
	v_lshrrev_b32_e32 v148, 3, v9
	s_addc_u32 s13, s7, 0
	v_and_b32_e32 v144, 0x70, v8
	v_mov_b32_e32 v145, 0
	v_lshlrev_b64 v[6:7], 11, v[4:5]
	v_or_b32_e32 v4, s10, v148
	s_waitcnt lgkmcnt(0)
	v_lshl_add_u64 v[2:3], s[12:13], 0, v[144:145]
	v_lshlrev_b64 v[4:5], 11, v[4:5]
	v_or_b32_e32 v10, 0x400, v0
	v_or_b32_e32 v11, 0x600, v0
	v_lshl_add_u64 v[6:7], v[2:3], 0, v[6:7]
	v_lshl_add_u64 v[4:5], v[2:3], 0, v[4:5]
	v_lshrrev_b32_e32 v150, 3, v10
	v_mov_b32_e32 v151, v145
	v_lshrrev_b32_e32 v152, 3, v11
	v_mov_b32_e32 v153, v145
	global_load_dwordx4 v[66:69], v[6:7], off
	global_load_dwordx4 v[70:73], v[4:5], off
	v_lshl_add_u64 v[4:5], s[10:11], 0, v[150:151]
	v_lshl_add_u64 v[6:7], s[10:11], 0, v[152:153]
	v_lshlrev_b64 v[4:5], 11, v[4:5]
	v_lshlrev_b64 v[6:7], 11, v[6:7]
	v_or_b32_e32 v12, 0x800, v0
	v_or_b32_e32 v13, 0xa00, v0
	v_lshl_add_u64 v[4:5], v[2:3], 0, v[4:5]
	v_lshl_add_u64 v[6:7], v[2:3], 0, v[6:7]
	v_lshrrev_b32_e32 v154, 3, v12
	v_mov_b32_e32 v155, v145
	v_lshrrev_b32_e32 v156, 3, v13
	v_mov_b32_e32 v157, v145
	global_load_dwordx4 v[74:77], v[4:5], off
	global_load_dwordx4 v[78:81], v[6:7], off
	v_lshl_add_u64 v[4:5], s[10:11], 0, v[154:155]
	v_lshl_add_u64 v[6:7], s[10:11], 0, v[156:157]
	v_lshlrev_b64 v[4:5], 11, v[4:5]
	v_lshlrev_b64 v[6:7], 11, v[6:7]
	v_lshl_add_u64 v[4:5], v[2:3], 0, v[4:5]
	v_lshl_add_u64 v[2:3], v[2:3], 0, v[6:7]
	s_lshl_b64 s[0:1], s[0:1], 14
	global_load_dwordx4 v[82:85], v[4:5], off
	global_load_dwordx4 v[86:89], v[2:3], off
	s_add_u32 s5, s68, s0
	v_mul_u32_u24_e32 v2, 0x556, v0
	s_addc_u32 s10, s69, s1
	s_lshl_b64 s[0:1], s[8:9], 1
	v_lshrrev_b32_e32 v2, 16, v2
	s_add_u32 s0, s5, s0
	v_mul_lo_u16_e32 v3, 48, v2
	s_addc_u32 s1, s10, s1
	v_sub_u16_e32 v4, v0, v3
	s_lshl_b32 s5, s14, 21
	v_lshl_or_b32 v2, v2, 15, s5
	v_mov_b32_e32 v3, v145
	v_lshlrev_b16_e32 v4, 3, v4
	v_lshl_add_u64 v[2:3], s[0:1], 0, v[2:3]
	v_lshlrev_b32_e32 v4, 1, v4
	v_mov_b32_e32 v5, v145
	v_lshl_add_u64 v[2:3], v[2:3], 0, v[4:5]
	v_mul_u32_u24_e32 v4, 0x556, v9
	v_lshrrev_b32_e32 v4, 16, v4
	v_mul_lo_u16_e32 v5, 48, v4
	v_sub_u16_e32 v6, v9, v5
	v_lshl_or_b32 v4, v4, 15, s5
	v_mov_b32_e32 v5, v145
	v_lshlrev_b16_e32 v6, 3, v6
	v_lshl_add_u64 v[4:5], s[0:1], 0, v[4:5]
	v_lshlrev_b32_e32 v6, 1, v6
	v_mov_b32_e32 v7, v145
	v_lshl_add_u64 v[4:5], v[4:5], 0, v[6:7]
	global_load_dwordx4 v[94:97], v[2:3], off
	global_load_dwordx4 v[90:93], v[4:5], off
	v_mul_u32_u24_e32 v2, 0x556, v10
	v_lshrrev_b32_e32 v2, 16, v2
	v_mul_lo_u16_e32 v3, 48, v2
	v_sub_u16_e32 v4, v10, v3
	v_lshl_or_b32 v2, v2, 15, s5
	v_mov_b32_e32 v3, v145
	v_lshlrev_b16_e32 v4, 3, v4
	v_lshl_add_u64 v[2:3], s[0:1], 0, v[2:3]
	v_lshlrev_b32_e32 v4, 1, v4
	v_mov_b32_e32 v5, v145
	v_lshl_add_u64 v[2:3], v[2:3], 0, v[4:5]
	v_mul_u32_u24_e32 v4, 0x556, v11
	v_lshrrev_b32_e32 v4, 16, v4
	v_mul_lo_u16_e32 v5, 48, v4
	v_sub_u16_e32 v6, v11, v5
	v_lshl_or_b32 v4, v4, 15, s5
	v_mov_b32_e32 v5, v145
	v_lshlrev_b16_e32 v6, 3, v6
	v_lshl_add_u64 v[4:5], s[0:1], 0, v[4:5]
	v_lshlrev_b32_e32 v6, 1, v6
	v_lshl_add_u64 v[4:5], v[4:5], 0, v[6:7]
	global_load_dwordx4 v[102:105], v[2:3], off
	global_load_dwordx4 v[98:101], v[4:5], off
	v_mul_u32_u24_e32 v2, 0xaab, v12
	v_lshrrev_b32_e32 v2, 17, v2
	v_mul_lo_u16_e32 v3, 48, v2
	v_sub_u16_e32 v4, v12, v3
	v_lshl_or_b32 v2, v2, 15, s5
	v_mov_b32_e32 v3, v145
	v_lshlrev_b16_e32 v4, 3, v4
	v_lshl_add_u64 v[2:3], s[0:1], 0, v[2:3]
	v_lshlrev_b32_e32 v4, 1, v4
	v_mov_b32_e32 v5, v145
	v_lshl_add_u64 v[2:3], v[2:3], 0, v[4:5]
	v_mul_u32_u24_e32 v4, 0xaab, v13
	v_lshrrev_b32_e32 v4, 17, v4
	v_mul_lo_u16_e32 v5, 48, v4
	v_sub_u16_e32 v6, v13, v5
	v_lshl_or_b32 v4, v4, 15, s5
	v_mov_b32_e32 v5, v145
	v_lshlrev_b16_e32 v6, 3, v6
	v_lshl_add_u64 v[4:5], s[0:1], 0, v[4:5]
	v_lshlrev_b32_e32 v6, 1, v6
; #define LAS __attribute__((address_space(3)))
; __device__ __forceinline__ void attn_phase(LAS unsigned char* lds, const bf16_t* Q, const bf16_t* Kb, const bf16_t* VT, const bf16_t* Zs, bf16_t* OZ, int vcu, int G) {
;     ...
;     u32x4 sk[6], sv[6];
;     ...
;     if (vcu < NU) ATT_LOAD_STAGE(vcu);
;     for (int unit = vcu; unit < NU; unit += G) {
;         ATT_DECODE(unit, h, rowbase, q0b, kw0)
;         const int qblk = unit & 31;
;         const int qb = 8 * qblk + w, q0 = 32 * qb;
;         bf16x8 qf[4];
;         { const bf16_t* qp = Q + (rowbase + q0 + ql) * D + h * 64 + 8 * hi;
; #pragma unroll
;           for (int kk = 0; kk < 4; ++kk) qf[kk] = *(const bf16x8*)(qp + 16 * kk); }
;         u32x2 zz[8];
;         { const bf16_t* zp = Zs + (rowbase + q0 + ql) * D + h * 64 + 4 * hi;
; #pragma unroll
;           for (int g4 = 0; g4 < 4; ++g4) { zz[g4] = *(const u32x2*)(zp + 8 * g4); zz[4 + g4] = *(const u32x2*)(zp + 32 + 8 * g4); } }
;         asm volatile("" ::: "memory");
; #pragma unroll
;         for (int i = 0; i < 6; ++i) { const int idx = tid + NTHR * i, r = idx >> 3, c = idx & 7;
;             *(LAS u32x4*)(KL + r * 128 + ((c ^ ((r >> 1) & 7)) << 4)) = sk[i]; }
; #pragma unroll
;         for (int i = 0; i < 6; ++i) { const int idx = tid + NTHR * i, d = idx / 48, ch = idx % 48;
;             { u32x4 v = sv[i]; const int gp = (2 * ch) ^ (d & 31);
;                 if (d & 1) { const u32x4 t = v; v.x = t.z; v.y = t.w; v.z = t.x; v.w = t.y; }
;                 *(LAS u32x4*)(VL + d * 768 + ((gp & ~1) << 3)) = v; } }
	v_lshl_add_u64 v[4:5], v[4:5], 0, v[6:7]
	global_load_dwordx4 v[110:113], v[2:3], off
	global_load_dwordx4 v[106:109], v[4:5], off
	s_movk_i32 s5, 0x3f80
	v_mov_b32_e32 v6, 0x2000
	v_bitop3_b32 v7, v8, s5, v6 bitop3:0xc8
	s_movk_i32 s5, 0x7f80
	v_mov_b32_e32 v6, 0x6000
	v_bitop3_b32 v15, v8, s5, v6 bitop3:0xc8
	s_mov_b32 s5, 0xbf80
	v_mov_b32_e32 v6, 0xa000
	s_mov_b32 s12, 0x5555556
	s_movk_i32 s4, 0x70
	v_bitop3_b32 v17, v8, s5, v6 bitop3:0xc8
	v_mul_hi_u32 v6, v0, s12
	v_bitop3_b32 v3, v8, s4, v0 bitop3:0x48
	v_and_b32_e32 v5, 0x1f80, v8
	v_mul_u32_u24_e32 v8, 48, v6
	v_sub_u32_e32 v8, v0, v8
	v_and_b32_e32 v14, 1, v6
	v_cmp_eq_u32_e64 s[48:49], 0, v14
	v_lshlrev_b32_e32 v14, 4, v8
	v_lshlrev_b32_e32 v16, 3, v6
	v_bitop3_b32 v19, v16, v14, s4 bitop3:0x6c
	v_mul_hi_u32 v14, v9, s12
	v_mul_u32_u24_e32 v16, 48, v14
	v_bfe_u32 v1, v0, 5, 1
	v_sub_u32_e32 v9, v9, v16
	v_and_b32_e32 v16, 1, v14
	v_lshlrev_b32_e32 v4, 2, v1
	s_movk_i32 s14, 0x300
	v_cmp_eq_u32_e64 s[4:5], 0, v16
	v_lshlrev_b32_e32 v16, 4, v9
	v_lshlrev_b32_e32 v21, 3, v14
	s_movk_i32 s15, 0xf0
	v_and_b32_e32 v142, 31, v0
	v_mad_u32_u24 v18, v6, s14, 0
	v_bitop3_b32 v21, v21, v16, s15 bitop3:0x6c
	v_mul_hi_u32 v16, v10, s12
	v_lshlrev_b32_e32 v196, 14, v6
	v_lshlrev_b32_e32 v6, 3, v8
	v_lshlrev_b32_e32 v8, 3, v9
	v_or_b32_e32 v9, 1, v4
	v_mul_u32_u24_e32 v22, 48, v16
	v_cmp_lt_u32_e64 s[16:17], v9, v142
	v_or_b32_e32 v9, 2, v4
	v_sub_u32_e32 v10, v10, v22
	v_cmp_lt_u32_e64 s[18:19], v9, v142
	v_or_b32_e32 v9, 3, v4
	v_lshlrev_b32_e32 v23, 4, v10
	v_lshlrev_b32_e32 v24, 3, v16
	v_cmp_lt_u32_e64 s[20:21], v9, v142
	v_or_b32_e32 v9, 8, v4
	v_bitop3_b32 v23, v24, v23, s15 bitop3:0x6c
	v_mul_hi_u32 v24, v11, s12
	v_cmp_lt_u32_e64 s[22:23], v9, v142
	v_or_b32_e32 v9, 9, v4
	v_mul_u32_u24_e32 v25, 48, v24
	v_cmp_lt_u32_e64 s[24:25], v9, v142
	v_or_b32_e32 v9, 10, v4
	v_sub_u32_e32 v11, v11, v25
	v_cmp_lt_u32_e64 s[26:27], v9, v142
	v_or_b32_e32 v9, 11, v4
	v_lshlrev_b32_e32 v26, 4, v11
	v_lshlrev_b32_e32 v27, 3, v24
	v_cmp_lt_u32_e64 s[28:29], v9, v142
	v_or_b32_e32 v9, 16, v4
	v_bitop3_b32 v26, v27, v26, s15 bitop3:0x6c
	v_mul_hi_u32 v27, v12, s12
	v_cmp_lt_u32_e64 s[30:31], v9, v142
	v_or_b32_e32 v9, 17, v4
	v_mul_u32_u24_e32 v28, 48, v27
	v_cmp_lt_u32_e64 s[34:35], v9, v142
	v_or_b32_e32 v9, 18, v4
	v_sub_u32_e32 v28, v12, v28
	v_and_b32_e32 v12, 1, v27
	v_cmp_lt_u32_e64 s[36:37], v9, v142
	v_or_b32_e32 v9, 19, v4
	v_cmp_eq_u32_e64 s[10:11], 0, v12
	v_lshlrev_b32_e32 v12, 4, v28
	v_lshlrev_b32_e32 v30, 3, v27
	v_mul_hi_u32 v31, v13, s12
	v_cmp_lt_u32_e64 s[38:39], v9, v142
	v_or_b32_e32 v9, 24, v4
	v_bitop3_b32 v30, v30, v12, s15 bitop3:0x6c
	v_mul_u32_u24_e32 v12, 48, v31
	v_cmp_lt_u32_e64 s[40:41], v9, v142
	v_or_b32_e32 v9, 25, v4
	v_sub_u32_e32 v13, v13, v12
	v_and_b32_e32 v12, 1, v31
	v_cmp_lt_u32_e64 s[42:43], v9, v142
	v_or_b32_e32 v9, 26, v4
	s_lshl_b32 s58, s85, 12
	v_lshlrev_b32_e32 v2, 3, v1
	v_lshl_add_u64 v[158:159], s[6:7], 0, v[144:145]
	v_lshlrev_b32_e32 v144, 4, v1
	v_and_b32_e32 v22, 1, v16
	v_and_b32_e32 v25, 1, v24
	v_cmp_eq_u32_e64 s[12:13], 0, v12
	v_lshlrev_b32_e32 v12, 4, v13
	v_lshlrev_b32_e32 v33, 3, v31
	v_cmp_lt_u32_e64 s[44:45], v9, v142
	v_or_b32_e32 v9, 27, v4
	s_add_i32 s58, s58, 0
	v_add_u32_e32 v3, 0, v3
	v_lshl_add_u64 v[160:161], s[6:7], 0, v[144:145]
	v_mad_u32_u24 v20, v14, s14, 0
	v_cmp_eq_u32_e64 s[6:7], 0, v22
	v_mad_u32_u24 v22, v16, s14, 0
	v_cmp_eq_u32_e64 s[8:9], 0, v25
	v_mad_u32_u24 v25, v24, s14, 0
	v_mad_u32_u24 v29, v27, s14, 0
	v_mad_u32_u24 v32, v31, s14, 0
	v_bitop3_b32 v33, v33, v12, s15 bitop3:0x6c
	v_lshlrev_b32_e32 v197, 14, v14
	v_lshlrev_b32_e32 v198, 14, v16
	v_lshlrev_b32_e32 v10, 3, v10
	v_lshlrev_b32_e32 v12, 3, v11
	v_lshlrev_b32_e32 v14, 3, v28
	v_lshlrev_b32_e32 v16, 3, v13
	v_mad_u32_u24 v202, v142, s14, 0
	v_cmp_lt_u32_e64 s[46:47], v9, v142
	v_lshl_add_u32 v9, v142, 7, s58
	v_lshlrev_b32_e32 v144, 1, v2
	v_mbcnt_lo_u32_b32 v2, -1, 0
	s_mov_b32 s73, 0
	v_or_b32_e32 v143, 2, v1
	v_or_b32_e32 v147, 4, v1
	v_or_b32_e32 v149, 6, v1
	v_cmp_eq_u32_e64 s[0:1], 0, v1
	v_lshlrev_b32_e32 v199, 14, v24
	v_lshlrev_b32_e32 v200, 14, v27
	v_lshlrev_b32_e32 v201, 14, v31
	v_add_u32_e32 v203, 0xc000, v202
	v_cmp_lt_u32_e64 s[14:15], v4, v142
	s_add_i32 s86, s85, 1
	s_lshl_b32 s87, s85, 5
	v_or_b32_e32 v204, 0xffffffe0, v142
	v_add_u32_e32 v205, 0xfffff000, v9
	v_lshlrev_b32_e32 v162, 1, v4
	v_add_u32_e32 v206, v3, v5
	v_add_u32_e32 v207, v3, v7
	v_add_u32_e32 v208, v3, v15
	v_add_u32_e32 v209, v3, v17
	v_add_u32_e32 v210, v18, v19
	v_add_u32_e32 v211, v20, v21
	v_add_u32_e32 v212, v22, v23
	v_add_u32_e32 v213, v25, v26
	v_add_u32_e32 v214, v29, v30
	v_add_u32_e32 v215, v32, v33
	v_lshlrev_b32_e32 v164, 1, v6
	v_lshlrev_b32_e32 v166, 1, v8
	v_lshlrev_b32_e32 v168, 1, v10
	v_lshlrev_b32_e32 v170, 1, v12
	v_lshlrev_b32_e32 v172, 1, v14
	v_lshlrev_b32_e32 v174, 1, v16
	s_mov_b32 s88, 0x1f800000
	v_mbcnt_hi_u32_b32 v216, -1, v2
	s_mov_b32 s89, s84
	s_branch .LBB0_540

; #define SEAM(k) do { if (IN(k) && IN((k) + 1)) xcd_barrier(xbar); } while (0)
; __device__ __forceinline__ void xcd_barrier(const XcdBarrier& b) {
;     asm volatile("s_waitcnt vmcnt(0)" ::: "memory");
;     __syncthreads();
;     if (threadIdx.x == 0) {
;         unsigned* bar = b.bar;
;         __builtin_amdgcn_s_waitcnt(0);
;         unsigned nloc = b.st[0], nx = b.st[1];
;         if (nloc == 0u) { xcd_barrier_complete(bar, b.x, nloc, nx); b.st[0] = nloc; b.st[1] = nx; }
; __global__ void __launch_bounds__(NTHR, 2) hybrid_fwd(Args a) {
;     ...
;     SEAM(7);
.LBB0_557:
	s_setprio 0
	s_cmp_gt_i32 s55, 8
	s_cselect_b64 s[0:1], -1, 0
	s_and_b64 s[4:5], s[70:71], s[0:1]
	s_andn2_b64 vcc, exec, s[4:5]
	s_cbranch_vccnz .LBB0_607
	s_waitcnt vmcnt(0)
	v_cmp_eq_u32_e32 vcc, 0, v0
	s_waitcnt vmcnt(0) lgkmcnt(0)
	s_barrier
	s_and_saveexec_b64 s[4:5], vcc
	s_cbranch_execz .LBB0_606
	s_add_i32 s6, 0, 0x23fc0
	v_mov_b32_e32 v1, s6
	s_waitcnt vmcnt(0) expcnt(0) lgkmcnt(0)
	ds_read_b32 v3, v1
	s_add_i32 s6, 0, 0x23fc4
	v_mov_b32_e32 v1, s6
	ds_read_b32 v1, v1
	s_waitcnt lgkmcnt(1)
	v_cmp_ne_u32_e32 vcc, 0, v3
	s_cbranch_vccnz .LBB0_574
	v_readlane_b32 s6, v253, 0
	v_readlane_b32 s7, v253, 1
	s_load_dwordx2 s[10:11], s[6:7], 0x4
	s_add_u32 s6, s52, 0x1000
	s_addc_u32 s7, s53, 0
	s_add_u32 s8, s52, 0x1100
	s_addc_u32 s9, s53, 0
	s_waitcnt lgkmcnt(0)
	s_mul_i32 s20, s10, s3
	s_add_u32 s10, s52, 0x1200
	s_mul_i32 s20, s20, s11
	s_addc_u32 s11, s53, 0
	s_add_u32 s12, s52, 0x1300
	s_addc_u32 s13, s53, 0
	s_mov_b32 s21, 1
	v_mov_b32_e32 v17, 0
	s_branch .LBB0_562
